# hand-written weight conversion loops in phases 8 and 7 (two tiles per iteration, 8 row loads in flight per thread)
# baseline (speedup 1.0000x reference)
; __device__ __forceinline__ void tjob_load(const TJob& j, int tile, f32x4 (&v)[4]) {
;     const int tid = threadIdx.x, nkt = j.K >> 7, tn = tile / nkt, tk = tile - tn * nkt;
;     const int n = tn * 64 + (tid & 15) * 4, kr = tid >> 4, col = map_col(j.map, n);
; #pragma unroll
;     for (int i = 0; i < 4; ++i) v[i] = col >= 0 ? __builtin_nontemporal_load((const f32x4*)(j.src + (size_t)(tk * 128 + kr + 32 * i) * j.ld_src + col)) : (f32x4){0.f, 0.f, 0.f, 0.f};
; }
; __device__ __forceinline__ void transpose_jobs(const TJob* jobs, int njobs, int bi, int nblk, LAS unsigned char* lds) {
;     ...
;     f32x4 v[4]; int curj = 0, base = 0;
;     int t = bi;
;     auto locate = [&](int tt, int& jj, int& bb) { while (tt >= bb + (jobs[jj].Nout >> 6) * (jobs[jj].K >> 7)) { bb += (jobs[jj].Nout >> 6) * (jobs[jj].K >> 7); ++jj; } };
;     if (t < total) { locate(t, curj, base); tjob_load(jobs[curj], t - base, v); }
;     while (t < total) {
;         const int tn = t + nblk; int nj = curj, nb = base; f32x4 w[4];
;         if (tn < total) { locate(tn, nj, nb); tjob_load(jobs[nj], tn - nb, w); }
;         tjob_store(jobs[curj], t - base, v, s);
;         if (tn < total) {
; #pragma unroll
;             for (int i = 0; i < 4; ++i) v[i] = w[i]; }
;         t = tn; curj = nj; base = nb;
;     }
.LBB0_1228:
	v_and_b32_e32 v38, 60, v184
	v_mul_u32_u24_e32 v0, 0x204, v129
	s_cmpk_gt_i32 s96, 0x88
	v_lshl_add_u32 v39, v166, 2, 0
	v_mul_u32_u24_e32 v40, 0x204, v38
	v_add3_u32 v41, 0, v0, v128
	s_cbranch_scc0 .LBB0_1241
	s_mov_b64 s[8:9], 0
	s_cmpk_gt_i32 s2, 0x87
	s_mov_b64 s[6:7], 0
	s_cbranch_scc0 .LBB0_1242
	s_cmpk_lg_u32 s96, 0x100
	s_cbranch_scc1 .Ltr7_compiled
	s_waitcnt vmcnt(0)
	s_load_dwordx4 s[8:11], s[0:1], 0x150
	v_and_b32_e32 v105, 15, v160
	v_lshrrev_b32_e32 v106, 4, v160
	v_lshrrev_b32_e32 v107, 3, v160
	v_and_b32_e32 v108, 7, v160
	v_mul_u32_u24_e32 v100, 0x2000, v106
	v_lshl_add_u32 v100, v105, 4, v100
	v_mul_u32_u24_e32 v102, 2064, v105
	v_lshl_add_u32 v102, v106, 2, v102
	v_mul_u32_u24_e32 v103, 516, v107
	v_lshl_add_u32 v103, v108, 6, v103
	v_add_u32_e32 v104, 0x8400, v103
	v_mul_u32_u24_e32 v101, 0x2c00, v107
	v_lshl_add_u32 v101, v108, 5, v101
	s_sub_i32 s12, s2, 136
	s_add_i32 s13, s12, 120
	s_waitcnt lgkmcnt(0)
	s_mul_i32 s50, s12, 1490
	s_lshr_b32 s50, s50, 16
	s_mul_i32 s51, s50, 44
	s_sub_i32 s51, s12, s51
	s_mul_i32 s51, s51, 0x100000
	s_lshl_b32 s52, s50, 6
	s_lshl_b32 s52, s52, 2
	s_add_u32 s51, s51, s52
	s_add_u32 s16, s8, s51
	s_addc_u32 s17, s9, 0
	s_add_u32 s18, s16, 0x40000
	s_addc_u32 s19, s17, 0
	s_add_u32 s20, s18, 0x40000
	s_addc_u32 s21, s19, 0
	s_add_u32 s22, s20, 0x40000
	s_addc_u32 s23, s21, 0
	global_load_dwordx4 v[32:35], v100, s[16:17] nt
	global_load_dwordx4 v[36:39], v100, s[18:19] nt
	global_load_dwordx4 v[40:43], v100, s[20:21] nt
	global_load_dwordx4 v[44:47], v100, s[22:23] nt
	s_mul_i32 s50, s13, 1490
	s_lshr_b32 s50, s50, 16
	s_mul_i32 s51, s50, 44
	s_sub_i32 s51, s13, s51
	s_mul_i32 s51, s51, 0x100000
	s_lshl_b32 s52, s50, 6
	s_lshl_b32 s52, s52, 2
	s_add_u32 s51, s51, s52
	s_add_u32 s24, s8, s51
	s_addc_u32 s25, s9, 0
	s_add_u32 s26, s24, 0x40000
	s_addc_u32 s27, s25, 0
	s_add_u32 s28, s26, 0x40000
	s_addc_u32 s29, s27, 0
	s_add_u32 s30, s28, 0x40000
	s_addc_u32 s31, s29, 0
	global_load_dwordx4 v[48:51], v100, s[24:25] nt
	global_load_dwordx4 v[52:55], v100, s[26:27] nt
	global_load_dwordx4 v[56:59], v100, s[28:29] nt
	global_load_dwordx4 v[60:63], v100, s[30:31] nt
	s_mov_b32 s14, 1
	s_mov_b32 s15, 0
.Ltr7_loop:
	s_cmp_eq_u32 s15, 4
	s_cbranch_scc1 .Ltr7_w4
	s_cmp_eq_u32 s15, 2
	s_cbranch_scc1 .Ltr7_w2
	s_waitcnt vmcnt(0)
	s_branch .Ltr7_wd
.Ltr7_w4:
	s_waitcnt vmcnt(4)
	s_branch .Ltr7_wd
.Ltr7_w2:
	s_waitcnt vmcnt(2)
.Ltr7_wd:
	v_mov_b32_e32 v0, v32
	v_mov_b32_e32 v1, v33
	v_mov_b32_e32 v2, v34
	v_mov_b32_e32 v3, v35
	v_mov_b32_e32 v4, v36
	v_mov_b32_e32 v5, v37
	v_mov_b32_e32 v6, v38
	v_mov_b32_e32 v7, v39
	v_mov_b32_e32 v8, v40
	v_mov_b32_e32 v9, v41
	v_mov_b32_e32 v10, v42
	v_mov_b32_e32 v11, v43
	v_mov_b32_e32 v12, v44
	v_mov_b32_e32 v13, v45
	v_mov_b32_e32 v14, v46
	v_mov_b32_e32 v15, v47
	v_mov_b32_e32 v16, v48
	v_mov_b32_e32 v17, v49
	v_mov_b32_e32 v18, v50
	v_mov_b32_e32 v19, v51
	v_mov_b32_e32 v20, v52
	v_mov_b32_e32 v21, v53
	v_mov_b32_e32 v22, v54
	v_mov_b32_e32 v23, v55
	v_mov_b32_e32 v24, v56
	v_mov_b32_e32 v25, v57
	v_mov_b32_e32 v26, v58
	v_mov_b32_e32 v27, v59
	v_mov_b32_e32 v28, v60
	v_mov_b32_e32 v29, v61
	v_mov_b32_e32 v30, v62
	v_mov_b32_e32 v31, v63
	s_mov_b32 s40, s12
	s_mov_b32 s41, s14
	s_add_i32 s43, s12, 120
	s_add_i32 s12, s12, 240
	s_add_i32 s13, s12, 120
	s_mov_b32 s14, 0
	s_mov_b32 s42, 0
	s_cmp_lt_u32 s12, 1408
	s_cbranch_scc0 .Ltr7_nold
	s_mov_b32 s42, 1
	s_mul_i32 s50, s12, 1490
	s_lshr_b32 s50, s50, 16
	s_mul_i32 s51, s50, 44
	s_sub_i32 s51, s12, s51
	s_mul_i32 s51, s51, 0x100000
	s_lshl_b32 s52, s50, 6
	s_lshl_b32 s52, s52, 2
	s_add_u32 s51, s51, s52
	s_add_u32 s16, s8, s51
	s_addc_u32 s17, s9, 0
	s_add_u32 s18, s16, 0x40000
	s_addc_u32 s19, s17, 0
	s_add_u32 s20, s18, 0x40000
	s_addc_u32 s21, s19, 0
	s_add_u32 s22, s20, 0x40000
	s_addc_u32 s23, s21, 0
	global_load_dwordx4 v[32:35], v100, s[16:17] nt
	global_load_dwordx4 v[36:39], v100, s[18:19] nt
	global_load_dwordx4 v[40:43], v100, s[20:21] nt
	global_load_dwordx4 v[44:47], v100, s[22:23] nt
	s_cmp_lt_u32 s13, 1408
	s_cbranch_scc0 .Ltr7_nold
	s_mov_b32 s14, 1
	s_mul_i32 s50, s13, 1490
	s_lshr_b32 s50, s50, 16
	s_mul_i32 s51, s50, 44
	s_sub_i32 s51, s13, s51
	s_mul_i32 s51, s51, 0x100000
	s_lshl_b32 s52, s50, 6
	s_lshl_b32 s52, s52, 2
	s_add_u32 s51, s51, s52
	s_add_u32 s24, s8, s51
	s_addc_u32 s25, s9, 0
	s_add_u32 s26, s24, 0x40000
	s_addc_u32 s27, s25, 0
	s_add_u32 s28, s26, 0x40000
	s_addc_u32 s29, s27, 0
	s_add_u32 s30, s28, 0x40000
	s_addc_u32 s31, s29, 0
	global_load_dwordx4 v[48:51], v100, s[24:25] nt
	global_load_dwordx4 v[52:55], v100, s[26:27] nt
	global_load_dwordx4 v[56:59], v100, s[28:29] nt
	global_load_dwordx4 v[60:63], v100, s[30:31] nt
; #define LAS __attribute__((address_space(3)))
; __device__ __forceinline__ u32x4 pack8(const float* f) { u32x4 w; w.x = pk2(f[0], f[1]); w.y = pk2(f[2], f[3]); w.z = pk2(f[4], f[5]); w.w = pk2(f[6], f[7]); return w; }
; __device__ __forceinline__ void tjob_store(const TJob& j, int tile, const f32x4 (&v)[4], LAS float* s) {
;     const int tid = threadIdx.x, nkt = j.K >> 7, tn = tile / nkt, tk = tile - tn * nkt;
;     const int nq = tid & 15, kr = tid >> 4;
;     __syncthreads();
; #pragma unroll
;     for (int i = 0; i < 4; ++i)
; #pragma unroll
;         for (int q = 0; q < 4; ++q) s[(4 * nq + q) * 129 + kr + 32 * i] = v[i][q];
;     __syncthreads();
;     const int n = tid >> 3, k16 = (tid & 7) * 16;
;     float f[16];
; #pragma unroll
;     for (int i = 0; i < 16; ++i) f[i] = s[n * 129 + k16 + i];
;     bf16_t* d = j.dst + (size_t)(tn * 64 + n) * j.ld_dst + tk * 128 + k16;
;     *(u32x4*)d = pack8(f); *(u32x4*)(d + 8) = pack8(f + 8);
; }
.Ltr7_nold:
	s_barrier
	ds_write_b32 v102, v0 offset:0
	ds_write_b32 v102, v1 offset:516
	ds_write_b32 v102, v2 offset:1032
	ds_write_b32 v102, v3 offset:1548
	ds_write_b32 v102, v4 offset:128
	ds_write_b32 v102, v5 offset:644
	ds_write_b32 v102, v6 offset:1160
	ds_write_b32 v102, v7 offset:1676
	ds_write_b32 v102, v8 offset:256
	ds_write_b32 v102, v9 offset:772
	ds_write_b32 v102, v10 offset:1288
	ds_write_b32 v102, v11 offset:1804
	ds_write_b32 v102, v12 offset:384
	ds_write_b32 v102, v13 offset:900
	ds_write_b32 v102, v14 offset:1416
	ds_write_b32 v102, v15 offset:1932
	s_cmp_eq_u32 s41, 0
	s_cbranch_scc1 .Ltr7_nowb
	ds_write_b32 v102, v16 offset:33792
	ds_write_b32 v102, v17 offset:34308
	ds_write_b32 v102, v18 offset:34824
	ds_write_b32 v102, v19 offset:35340
	ds_write_b32 v102, v20 offset:33920
	ds_write_b32 v102, v21 offset:34436
	ds_write_b32 v102, v22 offset:34952
	ds_write_b32 v102, v23 offset:35468
	ds_write_b32 v102, v24 offset:34048
	ds_write_b32 v102, v25 offset:34564
	ds_write_b32 v102, v26 offset:35080
	ds_write_b32 v102, v27 offset:35596
	ds_write_b32 v102, v28 offset:34176
	ds_write_b32 v102, v29 offset:34692
	ds_write_b32 v102, v30 offset:35208
	ds_write_b32 v102, v31 offset:35724
.Ltr7_nowb:
	s_waitcnt lgkmcnt(0)
	s_barrier
	ds_read2_b32 v[64:65], v103 offset0:0 offset1:1
	ds_read2_b32 v[66:67], v103 offset0:2 offset1:3
	ds_read2_b32 v[68:69], v103 offset0:4 offset1:5
	ds_read2_b32 v[70:71], v103 offset0:6 offset1:7
	ds_read2_b32 v[72:73], v103 offset0:8 offset1:9
	ds_read2_b32 v[74:75], v103 offset0:10 offset1:11
	ds_read2_b32 v[76:77], v103 offset0:12 offset1:13
	ds_read2_b32 v[78:79], v103 offset0:14 offset1:15
	s_mul_i32 s50, s40, 1490
	s_lshr_b32 s50, s50, 16
	s_mul_i32 s51, s50, 44
	s_sub_i32 s51, s40, s51
	s_mul_i32 s50, s50, 0xb0000
	s_lshl_b32 s51, s51, 8
	s_add_u32 s50, s50, s51
	s_add_u32 s48, s10, s50
	s_addc_u32 s49, s11, 0
	s_waitcnt lgkmcnt(0)
	v_cvt_pk_bf16_f32 v80, v64, v65
	v_cvt_pk_bf16_f32 v81, v66, v67
	v_cvt_pk_bf16_f32 v82, v68, v69
	v_cvt_pk_bf16_f32 v83, v70, v71
	v_cvt_pk_bf16_f32 v84, v72, v73
	v_cvt_pk_bf16_f32 v85, v74, v75
	v_cvt_pk_bf16_f32 v86, v76, v77
	v_cvt_pk_bf16_f32 v87, v78, v79
	global_store_dwordx4 v101, v[80:83], s[48:49]
	global_store_dwordx4 v101, v[84:87], s[48:49] offset:16
	s_mov_b32 s15, 2
	s_cmp_eq_u32 s41, 0
	s_cbranch_scc1 .Ltr7_nosb
	ds_read2_b32 v[64:65], v104 offset0:0 offset1:1
	ds_read2_b32 v[66:67], v104 offset0:2 offset1:3
	ds_read2_b32 v[68:69], v104 offset0:4 offset1:5
	ds_read2_b32 v[70:71], v104 offset0:6 offset1:7
	ds_read2_b32 v[72:73], v104 offset0:8 offset1:9
	ds_read2_b32 v[74:75], v104 offset0:10 offset1:11
	ds_read2_b32 v[76:77], v104 offset0:12 offset1:13
	ds_read2_b32 v[78:79], v104 offset0:14 offset1:15
	s_mul_i32 s50, s43, 1490
	s_lshr_b32 s50, s50, 16
	s_mul_i32 s51, s50, 44
	s_sub_i32 s51, s43, s51
	s_mul_i32 s50, s50, 0xb0000
	s_lshl_b32 s51, s51, 8
	s_add_u32 s50, s50, s51
	s_add_u32 s48, s10, s50
	s_addc_u32 s49, s11, 0
	s_waitcnt lgkmcnt(0)
	v_cvt_pk_bf16_f32 v88, v64, v65
	v_cvt_pk_bf16_f32 v89, v66, v67
	v_cvt_pk_bf16_f32 v90, v68, v69
	v_cvt_pk_bf16_f32 v91, v70, v71
	v_cvt_pk_bf16_f32 v92, v72, v73
	v_cvt_pk_bf16_f32 v93, v74, v75
	v_cvt_pk_bf16_f32 v94, v76, v77
	v_cvt_pk_bf16_f32 v95, v78, v79
	global_store_dwordx4 v101, v[88:91], s[48:49]
	global_store_dwordx4 v101, v[92:95], s[48:49] offset:16
	s_mov_b32 s15, 4
.Ltr7_nosb:
	s_cmp_lg_u32 s42, 0
	s_cbranch_scc1 .Ltr7_loop
	s_waitcnt vmcnt(0) lgkmcnt(0)
	s_barrier
	s_branch .LBB0_1323
.Ltr7_compiled:
	s_load_dwordx2 s[6:7], s[0:1], 0x164
	s_add_i32 s22, s2, 0xffffff78
	s_waitcnt lgkmcnt(0)
	s_ashr_i32 s3, s7, 6
	s_ashr_i32 s6, s6, 7
	s_mul_i32 s3, s6, s3
	s_cmp_ge_i32 s22, s3
	s_cbranch_scc1 .LBB0_1536
	s_add_u32 s10, s0, 0xffffffd8
	s_addc_u32 s11, s1, -1
	s_mov_b32 s6, 0
	s_mov_b32 s12, -1
	s_mov_b64 s[14:15], s[10:11]

; __device__ __forceinline__ int map_col(int map, int n) {
;     if (map == 1) { if (n < 4096) return n; if (n < 5120) return 4112 + (n - 4096); if (n < 9216) return 5136 + (n - 5120); if (n < 9232) return 4096 + (n - 9216); return -1; }
;     if (map == 2) { const int pn = n >> 8, w = n & 255; return w < 128 ? 128 * pn + w : DFF + 128 * pn + (w - 128); }
;     return n;
; }
; __device__ __forceinline__ void tjob_load(const TJob& j, int tile, f32x4 (&v)[4]) {
;     const int tid = threadIdx.x, nkt = j.K >> 7, tn = tile / nkt, tk = tile - tn * nkt;
;     const int n = tn * 64 + (tid & 15) * 4, kr = tid >> 4, col = map_col(j.map, n);
; #pragma unroll
;     for (int i = 0; i < 4; ++i) v[i] = col >= 0 ? __builtin_nontemporal_load((const f32x4*)(j.src + (size_t)(tk * 128 + kr + 32 * i) * j.ld_src + col)) : (f32x4){0.f, 0.f, 0.f, 0.f};
; }
; __global__ void __launch_bounds__(512, 2) fwd_megakernel(KArgs ka) {
;     ...
;             if (rep == 0) { const int nfull = 1088 % nblk; if (nfull == 0 || nfull >= nblk) transpose_jobs(ka.jobs + 2, 1, bid, nblk, lds); else if (bid >= nfull) transpose_jobs(ka.jobs + 2, 1, bid - nfull, nblk - nfull, lds); } }
.LBB0_1390:
	s_cmpk_lg_u32 s96, 0x100
	s_cbranch_scc1 .Ltr8_compiled
	s_cmpk_lt_u32 s2, 64
	s_cbranch_scc0 .Ltr8_go
	s_waitcnt lgkmcnt(0)
	s_branch .LBB0_1592
.Ltr8_go:
	s_waitcnt vmcnt(0)
	s_load_dwordx4 s[8:11], s[0:1], 0x128
	v_and_b32_e32 v105, 15, v160
	v_lshrrev_b32_e32 v106, 4, v160
	v_lshrrev_b32_e32 v107, 3, v160
	v_and_b32_e32 v108, 7, v160
	v_mul_u32_u24_e32 v100, 0xb000, v106
	v_lshl_add_u32 v100, v105, 4, v100
	v_mul_u32_u24_e32 v102, 2064, v105
	v_lshl_add_u32 v102, v106, 2, v102
	v_mul_u32_u24_e32 v103, 516, v107
	v_lshl_add_u32 v103, v108, 6, v103
	v_add_u32_e32 v104, 0x8400, v103
	v_mul_u32_u24_e32 v101, 0x1000, v107
	v_lshl_add_u32 v101, v108, 5, v101
	s_sub_i32 s12, s2, 64
	s_add_i32 s13, s12, 192
	s_waitcnt lgkmcnt(0)
	s_lshr_b32 s50, s12, 4
	s_and_b32 s51, s12, 15
	s_mul_i32 s51, s51, 0x580000
	s_lshr_b32 s52, s50, 2
	s_lshl_b32 s52, s52, 7
	s_and_b32 s53, s50, 1
	s_lshl_b32 s53, s53, 6
	s_add_i32 s52, s52, s53
	s_bfe_u32 s53, s50, 0x10001
	s_mul_i32 s53, s53, 5632
	s_add_i32 s52, s52, s53
	s_lshl_b32 s52, s52, 2
	s_add_u32 s51, s51, s52
	s_add_u32 s16, s8, s51
	s_addc_u32 s17, s9, 0
	s_add_u32 s18, s16, 0x160000
	s_addc_u32 s19, s17, 0
	s_add_u32 s20, s18, 0x160000
	s_addc_u32 s21, s19, 0
	s_add_u32 s22, s20, 0x160000
	s_addc_u32 s23, s21, 0
	global_load_dwordx4 v[32:35], v100, s[16:17] nt
	global_load_dwordx4 v[36:39], v100, s[18:19] nt
	global_load_dwordx4 v[40:43], v100, s[20:21] nt
	global_load_dwordx4 v[44:47], v100, s[22:23] nt
	s_lshr_b32 s50, s13, 4
	s_and_b32 s51, s13, 15
	s_mul_i32 s51, s51, 0x580000
	s_lshr_b32 s52, s50, 2
	s_lshl_b32 s52, s52, 7
	s_and_b32 s53, s50, 1
	s_lshl_b32 s53, s53, 6
	s_add_i32 s52, s52, s53
	s_bfe_u32 s53, s50, 0x10001
	s_mul_i32 s53, s53, 5632
	s_add_i32 s52, s52, s53
	s_lshl_b32 s52, s52, 2
	s_add_u32 s51, s51, s52
	s_add_u32 s24, s8, s51
	s_addc_u32 s25, s9, 0
	s_add_u32 s26, s24, 0x160000
	s_addc_u32 s27, s25, 0
	s_add_u32 s28, s26, 0x160000
	s_addc_u32 s29, s27, 0
	s_add_u32 s30, s28, 0x160000
	s_addc_u32 s31, s29, 0
	global_load_dwordx4 v[48:51], v100, s[24:25] nt
	global_load_dwordx4 v[52:55], v100, s[26:27] nt
	global_load_dwordx4 v[56:59], v100, s[28:29] nt
	global_load_dwordx4 v[60:63], v100, s[30:31] nt
	s_mov_b32 s14, 1
	s_mov_b32 s15, 0

; __device__ __forceinline__ void tjob_load(const TJob& j, int tile, f32x4 (&v)[4]) {
;     const int tid = threadIdx.x, nkt = j.K >> 7, tn = tile / nkt, tk = tile - tn * nkt;
;     const int n = tn * 64 + (tid & 15) * 4, kr = tid >> 4, col = map_col(j.map, n);
; #pragma unroll
;     for (int i = 0; i < 4; ++i) v[i] = col >= 0 ? __builtin_nontemporal_load((const f32x4*)(j.src + (size_t)(tk * 128 + kr + 32 * i) * j.ld_src + col)) : (f32x4){0.f, 0.f, 0.f, 0.f};
; __device__ __forceinline__ void transpose_jobs(const TJob* jobs, int njobs, int bi, int nblk, LAS unsigned char* lds) {
;     ...
;     while (t < total) {
;         const int tn = t + nblk; int nj = curj, nb = base; f32x4 w[4];
;         if (tn < total) { locate(tn, nj, nb); tjob_load(jobs[nj], tn - nb, w); }
;         tjob_store(jobs[curj], t - base, v, s);
;         if (tn < total) {
; #pragma unroll
;             for (int i = 0; i < 4; ++i) v[i] = w[i]; }
;         t = tn; curj = nj; base = nb;
.Ltr8_wd:
	v_mov_b32_e32 v0, v32
	v_mov_b32_e32 v1, v33
	v_mov_b32_e32 v2, v34
	v_mov_b32_e32 v3, v35
	v_mov_b32_e32 v4, v36
	v_mov_b32_e32 v5, v37
	v_mov_b32_e32 v6, v38
	v_mov_b32_e32 v7, v39
	v_mov_b32_e32 v8, v40
	v_mov_b32_e32 v9, v41
	v_mov_b32_e32 v10, v42
	v_mov_b32_e32 v11, v43
	v_mov_b32_e32 v12, v44
	v_mov_b32_e32 v13, v45
	v_mov_b32_e32 v14, v46
	v_mov_b32_e32 v15, v47
	v_mov_b32_e32 v16, v48
	v_mov_b32_e32 v17, v49
	v_mov_b32_e32 v18, v50
	v_mov_b32_e32 v19, v51
	v_mov_b32_e32 v20, v52
	v_mov_b32_e32 v21, v53
	v_mov_b32_e32 v22, v54
	v_mov_b32_e32 v23, v55
	v_mov_b32_e32 v24, v56
	v_mov_b32_e32 v25, v57
	v_mov_b32_e32 v26, v58
	v_mov_b32_e32 v27, v59
	v_mov_b32_e32 v28, v60
	v_mov_b32_e32 v29, v61
	v_mov_b32_e32 v30, v62
	v_mov_b32_e32 v31, v63
	s_mov_b32 s40, s12
	s_mov_b32 s41, s14
	s_add_i32 s43, s12, 192
	s_add_i32 s12, s12, 384
	s_add_i32 s13, s12, 192
	s_mov_b32 s14, 0
	s_mov_b32 s42, 0
	s_cmp_lt_u32 s12, 2816
	s_cbranch_scc0 .Ltr8_nold
	s_mov_b32 s42, 1
	s_lshr_b32 s50, s12, 4
	s_and_b32 s51, s12, 15
	s_mul_i32 s51, s51, 0x580000
	s_lshr_b32 s52, s50, 2
	s_lshl_b32 s52, s52, 7
	s_and_b32 s53, s50, 1
	s_lshl_b32 s53, s53, 6
	s_add_i32 s52, s52, s53
	s_bfe_u32 s53, s50, 0x10001
	s_mul_i32 s53, s53, 5632
	s_add_i32 s52, s52, s53
	s_lshl_b32 s52, s52, 2
	s_add_u32 s51, s51, s52
	s_add_u32 s16, s8, s51
	s_addc_u32 s17, s9, 0
	s_add_u32 s18, s16, 0x160000
	s_addc_u32 s19, s17, 0
	s_add_u32 s20, s18, 0x160000
	s_addc_u32 s21, s19, 0
	s_add_u32 s22, s20, 0x160000
	s_addc_u32 s23, s21, 0
	global_load_dwordx4 v[32:35], v100, s[16:17] nt
	global_load_dwordx4 v[36:39], v100, s[18:19] nt
	global_load_dwordx4 v[40:43], v100, s[20:21] nt
	global_load_dwordx4 v[44:47], v100, s[22:23] nt
	s_cmp_lt_u32 s13, 2816
	s_cbranch_scc0 .Ltr8_nold
	s_mov_b32 s14, 1
	s_lshr_b32 s50, s13, 4
	s_and_b32 s51, s13, 15
	s_mul_i32 s51, s51, 0x580000
	s_lshr_b32 s52, s50, 2
	s_lshl_b32 s52, s52, 7
	s_and_b32 s53, s50, 1
	s_lshl_b32 s53, s53, 6
	s_add_i32 s52, s52, s53
	s_bfe_u32 s53, s50, 0x10001
	s_mul_i32 s53, s53, 5632
	s_add_i32 s52, s52, s53
	s_lshl_b32 s52, s52, 2
	s_add_u32 s51, s51, s52
	s_add_u32 s24, s8, s51
	s_addc_u32 s25, s9, 0
	s_add_u32 s26, s24, 0x160000
	s_addc_u32 s27, s25, 0
	s_add_u32 s28, s26, 0x160000
	s_addc_u32 s29, s27, 0
	s_add_u32 s30, s28, 0x160000
	s_addc_u32 s31, s29, 0
	global_load_dwordx4 v[48:51], v100, s[24:25] nt
	global_load_dwordx4 v[52:55], v100, s[26:27] nt
	global_load_dwordx4 v[56:59], v100, s[28:29] nt
	global_load_dwordx4 v[60:63], v100, s[30:31] nt

; #define LAS __attribute__((address_space(3)))
; __device__ __forceinline__ u32x4 pack8(const float* f) { u32x4 w; w.x = pk2(f[0], f[1]); w.y = pk2(f[2], f[3]); w.z = pk2(f[4], f[5]); w.w = pk2(f[6], f[7]); return w; }
; __device__ __forceinline__ void tjob_store(const TJob& j, int tile, const f32x4 (&v)[4], LAS float* s) {
;     const int tid = threadIdx.x, nkt = j.K >> 7, tn = tile / nkt, tk = tile - tn * nkt;
;     const int nq = tid & 15, kr = tid >> 4;
;     __syncthreads();
; #pragma unroll
;     for (int i = 0; i < 4; ++i)
; #pragma unroll
;         for (int q = 0; q < 4; ++q) s[(4 * nq + q) * 129 + kr + 32 * i] = v[i][q];
;     __syncthreads();
;     const int n = tid >> 3, k16 = (tid & 7) * 16;
;     float f[16];
; #pragma unroll
;     for (int i = 0; i < 16; ++i) f[i] = s[n * 129 + k16 + i];
;     bf16_t* d = j.dst + (size_t)(tn * 64 + n) * j.ld_dst + tk * 128 + k16;
;     *(u32x4*)d = pack8(f); *(u32x4*)(d + 8) = pack8(f + 8);
; }
.Ltr8_nowb:
	s_waitcnt lgkmcnt(0)
	s_barrier
	ds_read2_b32 v[64:65], v103 offset0:0 offset1:1
	ds_read2_b32 v[66:67], v103 offset0:2 offset1:3
	ds_read2_b32 v[68:69], v103 offset0:4 offset1:5
	ds_read2_b32 v[70:71], v103 offset0:6 offset1:7
	ds_read2_b32 v[72:73], v103 offset0:8 offset1:9
	ds_read2_b32 v[74:75], v103 offset0:10 offset1:11
	ds_read2_b32 v[76:77], v103 offset0:12 offset1:13
	ds_read2_b32 v[78:79], v103 offset0:14 offset1:15
	s_lshr_b32 s50, s40, 4
	s_and_b32 s51, s40, 15
	s_lshl_b32 s50, s50, 18
	s_lshl_b32 s51, s51, 8
	s_add_u32 s50, s50, s51
	s_add_u32 s48, s10, s50
	s_addc_u32 s49, s11, 0
	s_waitcnt lgkmcnt(0)
	v_cvt_pk_bf16_f32 v80, v64, v65
	v_cvt_pk_bf16_f32 v81, v66, v67
	v_cvt_pk_bf16_f32 v82, v68, v69
	v_cvt_pk_bf16_f32 v83, v70, v71
	v_cvt_pk_bf16_f32 v84, v72, v73
	v_cvt_pk_bf16_f32 v85, v74, v75
	v_cvt_pk_bf16_f32 v86, v76, v77
	v_cvt_pk_bf16_f32 v87, v78, v79
	global_store_dwordx4 v101, v[80:83], s[48:49]
	global_store_dwordx4 v101, v[84:87], s[48:49] offset:16
	s_mov_b32 s15, 2
	s_cmp_eq_u32 s41, 0
	s_cbranch_scc1 .Ltr8_nosb
	ds_read2_b32 v[64:65], v104 offset0:0 offset1:1
	ds_read2_b32 v[66:67], v104 offset0:2 offset1:3
	ds_read2_b32 v[68:69], v104 offset0:4 offset1:5
	ds_read2_b32 v[70:71], v104 offset0:6 offset1:7
	ds_read2_b32 v[72:73], v104 offset0:8 offset1:9
	ds_read2_b32 v[74:75], v104 offset0:10 offset1:11
	ds_read2_b32 v[76:77], v104 offset0:12 offset1:13
	ds_read2_b32 v[78:79], v104 offset0:14 offset1:15
	s_lshr_b32 s50, s43, 4
	s_and_b32 s51, s43, 15
	s_lshl_b32 s50, s50, 18
	s_lshl_b32 s51, s51, 8
	s_add_u32 s50, s50, s51
	s_add_u32 s48, s10, s50
	s_addc_u32 s49, s11, 0
	s_waitcnt lgkmcnt(0)
	v_cvt_pk_bf16_f32 v88, v64, v65
	v_cvt_pk_bf16_f32 v89, v66, v67
	v_cvt_pk_bf16_f32 v90, v68, v69
	v_cvt_pk_bf16_f32 v91, v70, v71
	v_cvt_pk_bf16_f32 v92, v72, v73
	v_cvt_pk_bf16_f32 v93, v74, v75
	v_cvt_pk_bf16_f32 v94, v76, v77
	v_cvt_pk_bf16_f32 v95, v78, v79
	global_store_dwordx4 v101, v[88:91], s[48:49]
	global_store_dwordx4 v101, v[92:95], s[48:49] offset:16
	s_mov_b32 s15, 4
.Ltr8_nosb:
	s_cmp_lg_u32 s42, 0
	s_cbranch_scc1 .Ltr8_loop
	s_waitcnt lgkmcnt(0)
	s_barrier
	s_branch .LBB0_1592
